# P0 prologue hand-rewritten (w_in transpose 32 loads in flight + prefetch, rmsnorm gains hoisted), nt on once-read f32 input loads
# speedup vs baseline: 1.0251x; 1.0251x over previous
.LBB0_17:
	s_or_b64 exec, exec, s[0:1]
	v_readfirstlane_b32 s0, v171
	s_lshr_b32 s1, s0, 6
	v_and_b32_e32 v170, 63, v171
	v_writelane_b32 v254, s0, 43
	s_nop 0
	v_readlane_b32 s0, v254, 0
	s_lshl_b32 s0, s0, 3
	v_writelane_b32 v254, s1, 44
	s_add_i32 s2, s1, s0
	s_lshl_b32 s0, s76, 3
	v_writelane_b32 v254, s0, 45
	s_cmpk_gt_i32 s2, 0x31ff
	s_nop 0
	v_writelane_b32 v254, s1, 46
	s_mov_b32 s0, s2
	v_writelane_b32 v254, s0, 47
	s_nop 1
	v_writelane_b32 v254, s1, 48
	s_cbranch_scc1 .LBB0_39
	s_movk_i32 s5, 0x1200
	s_movk_i32 s6, 0xa00
	v_readlane_b32 s7, v254, 45
	v_readlane_b32 s8, v254, 47
	v_readlane_b32 s14, v254, 18
	v_readlane_b32 s15, v254, 19
	v_readlane_b32 s16, v254, 2
	v_readlane_b32 s17, v254, 3
	v_readlane_b32 s0, v254, 44
	v_and_b32_e32 v1, 31, v170
	v_lshlrev_b32_e32 v1, 2, v1
	v_lshrrev_b32_e32 v0, 5, v170
	s_mulk_i32 s0, 0x2200
	v_mul_u32_u24_e32 v2, 0xc800, v0
	v_add_u32_e32 v64, v2, v1
	s_mov_b32 s4, 0x19000
	v_add_u32_e32 v65, s4, v64
	v_add_u32_e32 v66, s4, v65
	v_add_u32_e32 v67, s4, v66
	v_add_u32_e32 v68, s4, v67
	v_add_u32_e32 v69, s4, v68
	v_add_u32_e32 v70, s4, v69
	v_add_u32_e32 v71, s4, v70
	v_add_u32_e32 v72, s4, v71
	v_add_u32_e32 v73, s4, v72
	v_add_u32_e32 v74, s4, v73
	v_add_u32_e32 v75, s4, v74
	v_add_u32_e32 v76, s4, v75
	v_add_u32_e32 v77, s4, v76
	v_add_u32_e32 v78, s4, v77
	v_add_u32_e32 v79, s4, v78
	v_add_u32_e32 v80, s4, v79
	v_add_u32_e32 v81, s4, v80
	v_add_u32_e32 v82, s4, v81
	v_add_u32_e32 v83, s4, v82
	v_add_u32_e32 v84, s4, v83
	v_add_u32_e32 v85, s4, v84
	v_add_u32_e32 v86, s4, v85
	v_add_u32_e32 v87, s4, v86
	v_add_u32_e32 v88, s4, v87
	v_add_u32_e32 v89, s4, v88
	v_add_u32_e32 v90, s4, v89
	v_add_u32_e32 v91, s4, v90
	v_add_u32_e32 v92, s4, v91
	v_add_u32_e32 v93, s4, v92
	v_add_u32_e32 v94, s4, v93
	v_add_u32_e32 v95, s4, v94
	v_mul_u32_u24_e32 v3, 0x84, v0
	v_add3_u32 v96, s0, v3, v1
	v_and_b32_e32 v4, 7, v170
	v_lshrrev_b32_e32 v5, 3, v170
	v_mul_u32_u24_e32 v6, 0x420, v4
	v_lshlrev_b32_e32 v7, 2, v5
	v_add3_u32 v97, s0, v6, v7
	v_mul_u32_u24_e32 v8, 0x1000, v5
	v_lshl_add_u32 v98, v4, 4, v8
	s_mov_b32 s4, 0x8000
	v_add_u32_e32 v99, s4, v98
	v_add_u32_e32 v100, s4, v99
	v_add_u32_e32 v101, s4, v100
	s_mov_b32 s31, 0

.LBB0_36:
	s_mul_i32 s0, s3, 0x320000
	s_lshl_b32 s1, s2, 2
	s_add_u32 s0, s0, s1
	s_add_u32 s20, s14, s0
	s_addc_u32 s21, s15, 0
	s_lshl_b32 s0, s3, 7
	s_lshl_b32 s1, s9, 12
	s_add_u32 s0, s0, s1
	s_add_u32 s22, s16, s0
	s_addc_u32 s23, s17, 0
	global_load_dword v32, v64, s[20:21] nt
	global_load_dword v33, v65, s[20:21] nt
	global_load_dword v34, v66, s[20:21] nt
	global_load_dword v35, v67, s[20:21] nt
	global_load_dword v36, v68, s[20:21] nt
	global_load_dword v37, v69, s[20:21] nt
	global_load_dword v38, v70, s[20:21] nt
	global_load_dword v39, v71, s[20:21] nt
	global_load_dword v40, v72, s[20:21] nt
	global_load_dword v41, v73, s[20:21] nt
	global_load_dword v42, v74, s[20:21] nt
	global_load_dword v43, v75, s[20:21] nt
	global_load_dword v44, v76, s[20:21] nt
	global_load_dword v45, v77, s[20:21] nt
	global_load_dword v46, v78, s[20:21] nt
	global_load_dword v47, v79, s[20:21] nt
	global_load_dword v48, v80, s[20:21] nt
	global_load_dword v49, v81, s[20:21] nt
	global_load_dword v50, v82, s[20:21] nt
	global_load_dword v51, v83, s[20:21] nt
	global_load_dword v52, v84, s[20:21] nt
	global_load_dword v53, v85, s[20:21] nt
	global_load_dword v54, v86, s[20:21] nt
	global_load_dword v55, v87, s[20:21] nt
	global_load_dword v56, v88, s[20:21] nt
	global_load_dword v57, v89, s[20:21] nt
	global_load_dword v58, v90, s[20:21] nt
	global_load_dword v59, v91, s[20:21] nt
	global_load_dword v60, v92, s[20:21] nt
	global_load_dword v61, v93, s[20:21] nt
	global_load_dword v62, v94, s[20:21] nt
	global_load_dword v63, v95, s[20:21] nt
	s_mov_b32 s30, 1
	s_cmp_eq_u32 s31, 0
	s_cbranch_scc1 .Lp0a_ladder_first
.Lp0a_finish:
	s_waitcnt lgkmcnt(0)
	ds_read2_b32 v[8:9], v97 offset1:8
	ds_read2_b32 v[10:11], v97 offset0:33 offset1:41
	ds_read2_b32 v[12:13], v97 offset0:66 offset1:74
	ds_read2_b32 v[14:15], v97 offset0:99 offset1:107
	ds_read2_b32 v[16:17], v97 offset0:132 offset1:140
	ds_read2_b32 v[18:19], v97 offset0:165 offset1:173
	ds_read2_b32 v[20:21], v97 offset0:198 offset1:206
	ds_read2_b32 v[22:23], v97 offset0:231 offset1:239
	s_waitcnt lgkmcnt(0)
	v_cvt_pk_bf16_f32 v24, v8, v10
	v_cvt_pk_bf16_f32 v25, v12, v14
	v_cvt_pk_bf16_f32 v26, v16, v18
	v_cvt_pk_bf16_f32 v27, v20, v22
	v_cvt_pk_bf16_f32 v28, v9, v11
	v_cvt_pk_bf16_f32 v29, v13, v15
	v_cvt_pk_bf16_f32 v30, v17, v19
	v_cvt_pk_bf16_f32 v31, v21, v23
	ds_read2_b32 v[102:103], v97 offset0:16 offset1:24
	ds_read2_b32 v[104:105], v97 offset0:49 offset1:57
	ds_read2_b32 v[106:107], v97 offset0:82 offset1:90
	ds_read2_b32 v[108:109], v97 offset0:115 offset1:123
	ds_read2_b32 v[110:111], v97 offset0:148 offset1:156
	ds_read2_b32 v[112:113], v97 offset0:181 offset1:189
	ds_read2_b32 v[114:115], v97 offset0:214 offset1:222
	ds_read2_b32 v[116:117], v97 offset0:247 offset1:255
	global_store_dwordx4 v98, v[24:27], s[24:25]
	global_store_dwordx4 v99, v[28:31], s[24:25]
	s_waitcnt lgkmcnt(0)
	v_cvt_pk_bf16_f32 v120, v102, v104
	v_cvt_pk_bf16_f32 v121, v106, v108
	v_cvt_pk_bf16_f32 v122, v110, v112
	v_cvt_pk_bf16_f32 v123, v114, v116
	v_cvt_pk_bf16_f32 v124, v103, v105
	v_cvt_pk_bf16_f32 v125, v107, v109
	v_cvt_pk_bf16_f32 v126, v111, v113
	v_cvt_pk_bf16_f32 v127, v115, v117
	global_store_dwordx4 v100, v[120:123], s[24:25]
	global_store_dwordx4 v101, v[124:127], s[24:25]
	s_cmp_eq_u32 s30, 0
	s_cbranch_scc1 .LBB0_39
	s_waitcnt vmcnt(28)
	ds_write_b32 v96, v32
	ds_write_b32 v96, v33 offset:264
	ds_write_b32 v96, v34 offset:528
	ds_write_b32 v96, v35 offset:792
	ds_write_b32 v96, v36 offset:1056
	ds_write_b32 v96, v37 offset:1320
	ds_write_b32 v96, v38 offset:1584
	ds_write_b32 v96, v39 offset:1848
	s_waitcnt vmcnt(20)
	ds_write_b32 v96, v40 offset:2112
	ds_write_b32 v96, v41 offset:2376
	ds_write_b32 v96, v42 offset:2640
	ds_write_b32 v96, v43 offset:2904
	ds_write_b32 v96, v44 offset:3168
	ds_write_b32 v96, v45 offset:3432
	ds_write_b32 v96, v46 offset:3696
	ds_write_b32 v96, v47 offset:3960
	s_waitcnt vmcnt(12)
	ds_write_b32 v96, v48 offset:4224
	ds_write_b32 v96, v49 offset:4488
	ds_write_b32 v96, v50 offset:4752
	ds_write_b32 v96, v51 offset:5016
	ds_write_b32 v96, v52 offset:5280
	ds_write_b32 v96, v53 offset:5544
	ds_write_b32 v96, v54 offset:5808
	ds_write_b32 v96, v55 offset:6072
	s_waitcnt vmcnt(4)
	ds_write_b32 v96, v56 offset:6336
	ds_write_b32 v96, v57 offset:6600
	ds_write_b32 v96, v58 offset:6864
	ds_write_b32 v96, v59 offset:7128
	ds_write_b32 v96, v60 offset:7392
	ds_write_b32 v96, v61 offset:7656
	ds_write_b32 v96, v62 offset:7920
	ds_write_b32 v96, v63 offset:8184
	s_branch .Lp0a_common
.Lp0a_ladder_first:
	s_waitcnt vmcnt(24)
	ds_write_b32 v96, v32
	ds_write_b32 v96, v33 offset:264
	ds_write_b32 v96, v34 offset:528
	ds_write_b32 v96, v35 offset:792
	ds_write_b32 v96, v36 offset:1056
	ds_write_b32 v96, v37 offset:1320
	ds_write_b32 v96, v38 offset:1584
	ds_write_b32 v96, v39 offset:1848
	s_waitcnt vmcnt(16)
	ds_write_b32 v96, v40 offset:2112
	ds_write_b32 v96, v41 offset:2376
	ds_write_b32 v96, v42 offset:2640
	ds_write_b32 v96, v43 offset:2904
	ds_write_b32 v96, v44 offset:3168
	ds_write_b32 v96, v45 offset:3432
	ds_write_b32 v96, v46 offset:3696
	ds_write_b32 v96, v47 offset:3960
	s_waitcnt vmcnt(8)
	ds_write_b32 v96, v48 offset:4224
	ds_write_b32 v96, v49 offset:4488
	ds_write_b32 v96, v50 offset:4752
	ds_write_b32 v96, v51 offset:5016
	ds_write_b32 v96, v52 offset:5280
	ds_write_b32 v96, v53 offset:5544
	ds_write_b32 v96, v54 offset:5808
	ds_write_b32 v96, v55 offset:6072
	s_waitcnt vmcnt(0)
	ds_write_b32 v96, v56 offset:6336
	ds_write_b32 v96, v57 offset:6600
	ds_write_b32 v96, v58 offset:6864
	ds_write_b32 v96, v59 offset:7128
	ds_write_b32 v96, v60 offset:7392
	ds_write_b32 v96, v61 offset:7656
	ds_write_b32 v96, v62 offset:7920
	ds_write_b32 v96, v63 offset:8184
.Lp0a_common:
	s_mov_b64 s[24:25], s[22:23]
	s_mov_b32 s31, 1
	s_add_i32 s8, s8, s7
	s_cmpk_gt_i32 s8, 0x31ff
	s_cbranch_scc0 .LBB0_19
	s_mov_b32 s30, 0
	s_branch .Lp0a_finish
.LBB0_39:
	v_readlane_b32 s0, v254, 47
	v_mbcnt_lo_u32_b32 v220, -1, 0
	v_lshlrev_b32_e32 v178, 3, v170
	v_lshlrev_b32_e32 v176, 4, v170
	s_cmpk_gt_i32 s0, 0x21ff
	s_cbranch_scc1 .LBB0_44
	v_readlane_b32 s14, v254, 16
	v_readlane_b32 s15, v254, 17
	v_readlane_b32 s20, v254, 6
	v_readlane_b32 s21, v254, 7
	v_readlane_b32 s22, v254, 8
	v_readlane_b32 s23, v254, 9
	v_readlane_b32 s24, v254, 2
	v_readlane_b32 s25, v254, 3
	v_readlane_b32 s7, v254, 45
	v_readlane_b32 s8, v254, 47
	s_mov_b32 s0, 0
	s_add_u32 s24, s24, 0x7c00000
	s_addc_u32 s25, s25, 0
	s_add_u32 s16, s14, 0x1000
	s_addc_u32 s17, s15, 0
	v_writelane_b32 v254, s0, 46
	v_writelane_b32 v254, s0, 48
	global_load_dwordx4 v[128:131], v176, s[14:15]
	global_load_dwordx4 v[132:135], v176, s[14:15] offset:1024
	global_load_dwordx4 v[136:139], v176, s[14:15] offset:2048
	global_load_dwordx4 v[140:143], v176, s[14:15] offset:3072
	global_load_dwordx4 v[144:147], v176, s[16:17]
	global_load_dwordx4 v[148:151], v176, s[16:17] offset:1024
	global_load_dwordx4 v[152:155], v176, s[16:17] offset:2048
	global_load_dwordx4 v[156:159], v176, s[16:17] offset:3072
	v_lshlrev_b32_e32 v40, 2, v170
	v_xor_b32_e32 v41, 8, v40
	v_xor_b32_e32 v42, 16, v40
	v_xor_b32_e32 v43, 32, v40
	v_xor_b32_e32 v44, 64, v40
	v_xor_b32_e32 v45, 0x80, v40
	v_xor_b32_e32 v40, 4, v40
	v_mov_b32_e32 v52, 0x358637bd
	v_mov_b32_e32 v53, 0x260
	s_mov_b32 s28, 0xf800000
	s_movk_i32 s31, 0x2200
	s_cmpk_eq_i32 s7, 0x800
	s_cselect_b32 s30, 1, 0
	s_cselect_b32 s31, 0x2000, s31
	s_mov_b32 s29, 0
	s_mov_b32 s5, 0
.Lp0r_issue:
	s_lshl_b32 s0, s8, 13
	s_cmpk_lt_i32 s8, 0x2000
	s_cselect_b64 s[10:11], s[20:21], s[22:23]
	s_cselect_b32 s1, 0, 0x4000000
	s_sub_u32 s0, s0, s1
	s_add_u32 s10, s10, s0
	s_addc_u32 s11, s11, 0
	s_add_u32 s12, s10, 0x1000
	s_addc_u32 s13, s11, 0
	s_lshl_b32 s0, s8, 12
	s_add_u32 s18, s24, s0
	s_addc_u32 s19, s25, 0
	global_load_dwordx4 v[0:3], v176, s[10:11] nt
	global_load_dwordx4 v[4:7], v176, s[10:11] offset:1024 nt
	global_load_dwordx4 v[8:11], v176, s[10:11] offset:2048 nt
	global_load_dwordx4 v[12:15], v176, s[10:11] offset:3072 nt
	global_load_dwordx4 v[16:19], v176, s[12:13] nt
	global_load_dwordx4 v[20:23], v176, s[12:13] offset:1024 nt
	global_load_dwordx4 v[24:27], v176, s[12:13] offset:2048 nt
	global_load_dwordx4 v[28:31], v176, s[12:13] offset:3072 nt
	s_mov_b32 s4, 1
	s_cmp_eq_u32 s5, 0
	s_cbranch_scc1 .Lp0r_first
.Lp0r_stores:
	global_store_dwordx2 v178, v[80:81], s[26:27]
	global_store_dwordx2 v178, v[82:83], s[26:27] offset:512
	global_store_dwordx2 v178, v[84:85], s[26:27] offset:1024
	global_store_dwordx2 v178, v[86:87], s[26:27] offset:1536
	global_store_dwordx2 v178, v[88:89], s[26:27] offset:2048
	global_store_dwordx2 v178, v[90:91], s[26:27] offset:2560
	global_store_dwordx2 v178, v[92:93], s[26:27] offset:3072
	global_store_dwordx2 v178, v[94:95], s[26:27] offset:3584
	s_cmp_eq_u32 s4, 1
	s_cbranch_scc0 .LBB0_44
	s_waitcnt vmcnt(15)
	v_pk_mul_f32 v[32:33], v[0:1], v[0:1]
	v_pk_fma_f32 v[32:33], v[2:3], v[2:3], v[32:33]
	s_waitcnt vmcnt(14)
	v_pk_fma_f32 v[32:33], v[4:5], v[4:5], v[32:33]
	v_pk_fma_f32 v[32:33], v[6:7], v[6:7], v[32:33]
	s_waitcnt vmcnt(13)
	v_pk_fma_f32 v[32:33], v[8:9], v[8:9], v[32:33]
	v_pk_fma_f32 v[32:33], v[10:11], v[10:11], v[32:33]
	s_waitcnt vmcnt(12)
	v_pk_fma_f32 v[32:33], v[12:13], v[12:13], v[32:33]
	v_pk_fma_f32 v[32:33], v[14:15], v[14:15], v[32:33]
	s_waitcnt vmcnt(11)
	v_pk_fma_f32 v[32:33], v[16:17], v[16:17], v[32:33]
	v_pk_fma_f32 v[32:33], v[18:19], v[18:19], v[32:33]
	s_waitcnt vmcnt(10)
	v_pk_fma_f32 v[32:33], v[20:21], v[20:21], v[32:33]
	v_pk_fma_f32 v[32:33], v[22:23], v[22:23], v[32:33]
	s_waitcnt vmcnt(9)
	v_pk_fma_f32 v[32:33], v[24:25], v[24:25], v[32:33]
	v_pk_fma_f32 v[32:33], v[26:27], v[26:27], v[32:33]
	s_waitcnt vmcnt(8)
	v_pk_fma_f32 v[32:33], v[28:29], v[28:29], v[32:33]
	v_pk_fma_f32 v[32:33], v[30:31], v[30:31], v[32:33]
	s_branch .Lp0r_compute
.Lp0r_first:
	s_waitcnt vmcnt(7)
	v_pk_mul_f32 v[32:33], v[0:1], v[0:1]
	v_pk_fma_f32 v[32:33], v[2:3], v[2:3], v[32:33]
	s_waitcnt vmcnt(6)
	v_pk_fma_f32 v[32:33], v[4:5], v[4:5], v[32:33]
	v_pk_fma_f32 v[32:33], v[6:7], v[6:7], v[32:33]
	s_waitcnt vmcnt(5)
	v_pk_fma_f32 v[32:33], v[8:9], v[8:9], v[32:33]
	v_pk_fma_f32 v[32:33], v[10:11], v[10:11], v[32:33]
	s_waitcnt vmcnt(4)
	v_pk_fma_f32 v[32:33], v[12:13], v[12:13], v[32:33]
	v_pk_fma_f32 v[32:33], v[14:15], v[14:15], v[32:33]
	s_waitcnt vmcnt(3)
	v_pk_fma_f32 v[32:33], v[16:17], v[16:17], v[32:33]
	v_pk_fma_f32 v[32:33], v[18:19], v[18:19], v[32:33]
	s_waitcnt vmcnt(2)
	v_pk_fma_f32 v[32:33], v[20:21], v[20:21], v[32:33]
	v_pk_fma_f32 v[32:33], v[22:23], v[22:23], v[32:33]
	s_waitcnt vmcnt(1)
	v_pk_fma_f32 v[32:33], v[24:25], v[24:25], v[32:33]
	v_pk_fma_f32 v[32:33], v[26:27], v[26:27], v[32:33]
	s_waitcnt vmcnt(0)
	v_pk_fma_f32 v[32:33], v[28:29], v[28:29], v[32:33]
	v_pk_fma_f32 v[32:33], v[30:31], v[30:31], v[32:33]
.Lp0r_compute:
	s_mov_b32 s5, 1
	s_nop 0
	v_add_f32_e32 v58, v32, v33
	ds_bpermute_b32 v59, v40, v58
	s_waitcnt lgkmcnt(0)
	v_add_f32_e32 v58, v58, v59
	ds_bpermute_b32 v59, v41, v58
	s_waitcnt lgkmcnt(0)
	v_add_f32_e32 v58, v58, v59
	ds_bpermute_b32 v59, v42, v58
	s_waitcnt lgkmcnt(0)
	v_add_f32_e32 v58, v58, v59
	ds_bpermute_b32 v59, v43, v58
	s_waitcnt lgkmcnt(0)
	v_add_f32_e32 v58, v58, v59
	ds_bpermute_b32 v59, v44, v58
	s_waitcnt lgkmcnt(0)
	v_add_f32_e32 v58, v58, v59
	ds_bpermute_b32 v59, v45, v58
	s_waitcnt lgkmcnt(0)
	v_add_f32_e32 v58, v58, v59
	v_fmamk_f32 v58, v58, 0x3a000000, v52
	v_mul_f32_e32 v59, 0x4f800000, v58
	v_cmp_gt_f32_e32 vcc, s28, v58
	s_nop 1
	v_cndmask_b32_e32 v58, v58, v59, vcc
	v_sqrt_f32_e32 v59, v58
	s_nop 0
	v_add_u32_e32 v60, -1, v59
	v_add_u32_e32 v61, 1, v59
	v_fma_f32 v62, -v60, v59, v58
	v_fma_f32 v63, -v61, v59, v58
	v_cmp_ge_f32_e64 s[0:1], 0, v62
	s_nop 1
	v_cndmask_b32_e64 v59, v59, v60, s[0:1]
	v_cmp_lt_f32_e64 s[0:1], 0, v63
	s_nop 1
	v_cndmask_b32_e64 v59, v59, v61, s[0:1]
	v_mul_f32_e32 v60, 0x37800000, v59
	v_cndmask_b32_e32 v59, v59, v60, vcc
	v_cmp_class_f32_e32 vcc, v58, v53
	s_nop 1
	v_cndmask_b32_e32 v60, v59, v58, vcc
	v_div_scale_f32 v61, s[0:1], v60, v60, 1.0
	v_rcp_f32_e32 v62, v61
	v_div_scale_f32 v63, vcc, 1.0, v60, 1.0
	s_nop 0
	v_fma_f32 v64, -v61, v62, 1.0
	v_fmac_f32_e32 v62, v64, v62
	v_mul_f32_e32 v64, v63, v62
	v_fma_f32 v65, -v61, v64, v63
	v_fmac_f32_e32 v64, v65, v62
	v_fma_f32 v61, -v61, v64, v63
	v_div_fmas_f32 v61, v61, v62, v64
	v_div_fixup_f32 v60, v61, v60, 1.0
	v_pk_mul_f32 v[66:67], v[0:1], v[60:61] op_sel_hi:[1,0]
	v_pk_mul_f32 v[68:69], v[2:3], v[60:61] op_sel_hi:[1,0]
	v_pk_mul_f32 v[66:67], v[128:129], v[66:67]
	v_pk_mul_f32 v[68:69], v[130:131], v[68:69]
	v_cvt_pk_bf16_f32 v80, v66, v67
	v_cvt_pk_bf16_f32 v81, v68, v69
	v_pk_mul_f32 v[66:67], v[4:5], v[60:61] op_sel_hi:[1,0]
	v_pk_mul_f32 v[68:69], v[6:7], v[60:61] op_sel_hi:[1,0]
	v_pk_mul_f32 v[66:67], v[132:133], v[66:67]
	v_pk_mul_f32 v[68:69], v[134:135], v[68:69]
	v_cvt_pk_bf16_f32 v82, v66, v67
	v_cvt_pk_bf16_f32 v83, v68, v69
	v_pk_mul_f32 v[66:67], v[8:9], v[60:61] op_sel_hi:[1,0]
	v_pk_mul_f32 v[68:69], v[10:11], v[60:61] op_sel_hi:[1,0]
	v_pk_mul_f32 v[66:67], v[136:137], v[66:67]
	v_pk_mul_f32 v[68:69], v[138:139], v[68:69]
	v_cvt_pk_bf16_f32 v84, v66, v67
	v_cvt_pk_bf16_f32 v85, v68, v69
	v_pk_mul_f32 v[66:67], v[12:13], v[60:61] op_sel_hi:[1,0]
	v_pk_mul_f32 v[68:69], v[14:15], v[60:61] op_sel_hi:[1,0]
	v_pk_mul_f32 v[66:67], v[140:141], v[66:67]
	v_pk_mul_f32 v[68:69], v[142:143], v[68:69]
	v_cvt_pk_bf16_f32 v86, v66, v67
	v_cvt_pk_bf16_f32 v87, v68, v69
	v_pk_mul_f32 v[66:67], v[16:17], v[60:61] op_sel_hi:[1,0]
	v_pk_mul_f32 v[68:69], v[18:19], v[60:61] op_sel_hi:[1,0]
	v_pk_mul_f32 v[66:67], v[144:145], v[66:67]
	v_pk_mul_f32 v[68:69], v[146:147], v[68:69]
	v_cvt_pk_bf16_f32 v88, v66, v67
	v_cvt_pk_bf16_f32 v89, v68, v69
	v_pk_mul_f32 v[66:67], v[20:21], v[60:61] op_sel_hi:[1,0]
	v_pk_mul_f32 v[68:69], v[22:23], v[60:61] op_sel_hi:[1,0]
	v_pk_mul_f32 v[66:67], v[148:149], v[66:67]
	v_pk_mul_f32 v[68:69], v[150:151], v[68:69]
	v_cvt_pk_bf16_f32 v90, v66, v67
	v_cvt_pk_bf16_f32 v91, v68, v69
	v_pk_mul_f32 v[66:67], v[24:25], v[60:61] op_sel_hi:[1,0]
	v_pk_mul_f32 v[68:69], v[26:27], v[60:61] op_sel_hi:[1,0]
	v_pk_mul_f32 v[66:67], v[152:153], v[66:67]
	v_pk_mul_f32 v[68:69], v[154:155], v[68:69]
	v_cvt_pk_bf16_f32 v92, v66, v67
	v_cvt_pk_bf16_f32 v93, v68, v69
	v_pk_mul_f32 v[66:67], v[28:29], v[60:61] op_sel_hi:[1,0]
	v_pk_mul_f32 v[68:69], v[30:31], v[60:61] op_sel_hi:[1,0]
	v_pk_mul_f32 v[66:67], v[156:157], v[66:67]
	v_pk_mul_f32 v[68:69], v[158:159], v[68:69]
	v_cvt_pk_bf16_f32 v94, v66, v67
	v_cvt_pk_bf16_f32 v95, v68, v69
	s_mov_b64 s[26:27], s[18:19]
	s_add_i32 s8, s8, s7
	s_cmp_lt_i32 s8, s31
	s_cbranch_scc1 .Lp0r_issue
	s_cmp_eq_u32 s30, 0
	s_cbranch_scc1 .Lp0r_nonext
	s_cmp_eq_u32 s29, 1
	s_cbranch_scc1 .Lp0r_nonext
	s_mov_b32 s29, 1
	v_readlane_b32 s0, v254, 47
	s_nop 0
	s_cmpk_lt_i32 s0, 0x600
	s_cbranch_scc1 .Lp0r_nonext
	s_add_i32 s8, s0, 0x1a00
	s_branch .Lp0r_issue
.Lp0r_nonext:
	s_mov_b32 s4, 0
	s_branch .Lp0r_stores
